# residual-stream tile loads of the residual epilogue non-temporal (each tile is read once, then rewritten)
# baseline (speedup 1.0000x reference)
.LBB0_633:
	s_and_b64 vcc, exec, s[6:7]
	s_cbranch_vccz .LBB0_652
	s_cmp_eq_u32 s47, 2
	s_mov_b64 s[74:75], -1
	s_cbranch_scc0 .LBB0_652
	s_lshl_b32 s74, s15, 8
	s_lshl_b32 s1, s48, 8
	s_ashr_i32 s75, s74, 31
	s_or_b32 s1, s1, s58
	s_lshl_b64 s[6:7], s[74:75], 11
	v_lshl_add_u32 v128, v221, 3, s1
	s_add_u32 s6, s76, s6
	s_addc_u32 s7, s77, s7
	s_waitcnt lgkmcnt(0)
	v_ashrrev_i32_e32 v129, 31, v128
	v_ashrrev_i32_e32 v171, 31, v170
	v_lshl_add_u64 v[152:153], v[128:129], 1, s[6:7]
	v_lshlrev_b64 v[128:129], 11, v[170:171]
	v_lshl_add_u64 v[184:185], v[152:153], 0, v[128:129]
	global_load_dwordx4 v[176:179], v[184:185], off nt
	global_load_dwordx4 v[180:183], v[184:185], off offset:256 nt
	s_mov_b32 s1, 0x8000
	v_add_co_u32_e32 v128, vcc, s1, v184
	s_mov_b32 s1, 0x10000
	s_nop 0
	v_addc_co_u32_e32 v129, vcc, 0, v185, vcc
	v_add_co_u32_e32 v130, vcc, s1, v184
	s_mov_b64 s[6:7], 0x8000
	s_nop 0
	v_addc_co_u32_e32 v131, vcc, 0, v185, vcc
	s_mov_b32 s1, 0x18000
	v_lshl_add_u64 v[172:173], v[184:185], 0, s[6:7]
	s_mov_b64 s[6:7], 0x10000
	v_add_co_u32_e32 v132, vcc, s1, v184
	v_lshl_add_u64 v[174:175], v[184:185], 0, s[6:7]
	s_mov_b64 s[6:7], 0x18000
	v_addc_co_u32_e32 v133, vcc, 0, v185, vcc
	v_lshl_add_u64 v[154:155], v[184:185], 0, s[6:7]
	global_load_dwordx4 v[148:151], v[128:129], off nt
	global_load_dwordx4 v[144:147], v[172:173], off offset:256 nt
	global_load_dwordx4 v[136:139], v[174:175], off offset:256 nt
	global_load_dwordx4 v[140:143], v[130:131], off nt
	s_nop 0
	global_load_dwordx4 v[132:135], v[132:133], off nt
	s_nop 0
	global_load_dwordx4 v[128:131], v[154:155], off offset:256 nt
	v_cmp_eq_u32_e64 s[6:7], 0, v221
	s_waitcnt vmcnt(0)
	v_lshlrev_b32_e32 v188, 16, v176
	v_and_b32_e32 v189, 0xffff0000, v176
	v_lshlrev_b32_e32 v176, 16, v177
	v_and_b32_e32 v177, 0xffff0000, v177
	v_lshlrev_b32_e32 v190, 16, v178
	v_and_b32_e32 v191, 0xffff0000, v178
	v_lshlrev_b32_e32 v178, 16, v179
	v_and_b32_e32 v179, 0xffff0000, v179
	v_lshlrev_b32_e32 v192, 16, v180
	v_and_b32_e32 v193, 0xffff0000, v180
	v_lshlrev_b32_e32 v180, 16, v181
	v_and_b32_e32 v181, 0xffff0000, v181
	v_lshlrev_b32_e32 v222, 16, v182
	v_and_b32_e32 v223, 0xffff0000, v182
	v_lshlrev_b32_e32 v182, 16, v183
	v_and_b32_e32 v183, 0xffff0000, v183
	v_pk_fma_f32 v[224:225], s[90:91], v[122:123], v[176:177]
	v_pk_fma_f32 v[188:189], s[86:87], v[120:121], v[188:189]
	v_pk_fma_f32 v[226:227], s[90:91], v[114:115], v[178:179]
	v_pk_fma_f32 v[178:179], s[86:87], v[112:113], v[190:191]
	v_pk_fma_f32 v[180:181], s[90:91], v[126:127], v[180:181]
	v_pk_fma_f32 v[190:191], s[86:87], v[124:125], v[192:193]
	v_pk_fma_f32 v[182:183], s[90:91], v[118:119], v[182:183]
	v_pk_fma_f32 v[192:193], s[86:87], v[116:117], v[222:223]
	v_mul_f32_e32 v156, v189, v189
	v_mul_f32_e32 v187, v225, v225
	v_mul_f32_e32 v222, v179, v179
	v_mul_f32_e32 v223, v227, v227
	v_cvt_pk_bf16_f32 v176, v188, v189
	v_cvt_pk_bf16_f32 v177, v224, v225
	v_mul_f32_e32 v189, v191, v191
	v_mul_f32_e32 v225, v181, v181
	v_mul_f32_e32 v228, v193, v193
	v_mul_f32_e32 v229, v183, v183
	v_fmac_f32_e32 v156, v188, v188
	v_fmac_f32_e32 v187, v224, v224
	v_fmac_f32_e32 v222, v178, v178
	v_fmac_f32_e32 v223, v226, v226
	v_fmac_f32_e32 v189, v190, v190
	v_fmac_f32_e32 v225, v180, v180
	v_fmac_f32_e32 v228, v192, v192
	v_fmac_f32_e32 v229, v182, v182
	v_add_f32_e32 v156, v156, v187
	v_add_f32_e32 v187, v222, v223
	v_add_f32_e32 v188, v189, v225
	v_add_f32_e32 v189, v228, v229
	v_add_f32_e32 v156, v156, v187
	v_add_f32_e32 v187, v188, v189
	v_add_f32_e32 v156, v156, v187
	ds_bpermute_b32 v187, v218, v156
	v_cvt_pk_bf16_f32 v178, v178, v179
	v_cvt_pk_bf16_f32 v179, v226, v227
	global_store_dwordx4 v[184:185], v[176:179], off
	s_waitcnt lgkmcnt(0)
	v_add_f32_e32 v156, v156, v187
	ds_bpermute_b32 v176, v219, v156
	v_cvt_pk_bf16_f32 v178, v190, v191
	v_cvt_pk_bf16_f32 v179, v180, v181
	v_cvt_pk_bf16_f32 v180, v192, v193
	v_cvt_pk_bf16_f32 v181, v182, v183
	global_store_dwordx4 v[184:185], v[178:181], off offset:256
	s_and_saveexec_b64 vcc, s[6:7]
	s_cbranch_execz .LBB0_637
	s_waitcnt lgkmcnt(0)
	v_add_f32_e32 v156, v156, v176
	v_mul_f32_e32 v156, 0x4b800000, v156
	v_trunc_f32_e32 v156, v156
	v_mul_f32_e32 v176, 0x2f800000, v156
	v_floor_f32_e32 v177, v176
	v_fmac_f32_e32 v156, 0xcf800000, v177
	v_cvt_u32_f32_e32 v176, v156
	v_cvt_u32_f32_e32 v177, v177
	v_add_u32_e32 v178, s74, v170
	v_ashrrev_i32_e32 v179, 31, v178
	v_lshl_add_u64 v[178:179], v[178:179], 3, s[78:79]
	global_atomic_add_x2 v[178:179], v[176:177], off

.LBB0_643:
	s_or_b64 exec, exec, s[74:75]
	s_waitcnt lgkmcnt(0)
	v_lshlrev_b64 v[128:129], 11, v[170:171]
	v_lshl_add_u64 v[128:129], v[152:153], 0, v[128:129]
	v_add_co_u32_e32 v188, vcc, 0x40000, v128
	s_mov_b64 s[34:35], 0x40000
	s_nop 0
	v_addc_co_u32_e32 v189, vcc, 0, v129, vcc
	v_lshl_add_u64 v[180:181], v[128:129], 0, s[34:35]
	global_load_dwordx4 v[182:185], v[188:189], off nt
	global_load_dwordx4 v[152:155], v[180:181], off offset:256 nt
	v_add_co_u32_e32 v130, vcc, 0x48000, v128
	s_mov_b64 s[34:35], 0x48000
	s_nop 0
	v_addc_co_u32_e32 v131, vcc, 0, v129, vcc
	v_lshl_add_u64 v[178:179], v[128:129], 0, s[34:35]
	global_load_dwordx4 v[148:151], v[130:131], off nt
	global_load_dwordx4 v[144:147], v[178:179], off offset:256 nt
	s_mov_b64 s[34:35], 0x50000
	v_add_co_u32_e32 v130, vcc, 0x50000, v128
	v_lshl_add_u64 v[176:177], v[128:129], 0, s[34:35]
	s_nop 0
	v_addc_co_u32_e32 v131, vcc, 0, v129, vcc
	s_mov_b64 s[34:35], 0x58000
	v_lshl_add_u64 v[174:175], v[128:129], 0, s[34:35]
	v_add_co_u32_e32 v128, vcc, 0x58000, v128
	global_load_dwordx4 v[140:143], v[130:131], off nt
	global_load_dwordx4 v[136:139], v[176:177], off offset:256 nt
	v_addc_co_u32_e32 v129, vcc, 0, v129, vcc
	global_load_dwordx4 v[132:135], v[128:129], off nt
	s_nop 0
	global_load_dwordx4 v[128:131], v[174:175], off offset:256 nt
	s_waitcnt vmcnt(7)
	v_lshlrev_b32_e32 v190, 16, v182
	v_and_b32_e32 v191, 0xffff0000, v182
	v_lshlrev_b32_e32 v182, 16, v183
	v_and_b32_e32 v183, 0xffff0000, v183
	v_pk_fma_f32 v[222:223], s[90:91], v[58:59], v[182:183]
	v_pk_fma_f32 v[182:183], s[86:87], v[56:57], v[190:191]
	v_lshlrev_b32_e32 v192, 16, v184
	v_and_b32_e32 v193, 0xffff0000, v184
	v_lshlrev_b32_e32 v184, 16, v185
	v_and_b32_e32 v185, 0xffff0000, v185
	v_mul_f32_e32 v156, v183, v183
	v_mul_f32_e32 v171, v223, v223
	v_pk_fma_f32 v[190:191], s[90:91], v[50:51], v[184:185]
	v_pk_fma_f32 v[184:185], s[86:87], v[48:49], v[192:193]
	v_fmac_f32_e32 v156, v182, v182
	v_fmac_f32_e32 v171, v222, v222
	v_add_f32_e32 v156, v156, v171
	v_mul_f32_e32 v171, v185, v185
	v_mul_f32_e32 v187, v191, v191
	v_cvt_pk_bf16_f32 v182, v182, v183
	v_cvt_pk_bf16_f32 v183, v222, v223
	v_fmac_f32_e32 v171, v184, v184
	v_fmac_f32_e32 v187, v190, v190
	v_cvt_pk_bf16_f32 v184, v184, v185
	v_cvt_pk_bf16_f32 v185, v190, v191
	global_store_dwordx4 v[188:189], v[182:185], off
	v_add_f32_e32 v171, v171, v187
	v_add_f32_e32 v156, v156, v171
	s_waitcnt vmcnt(7)
	v_lshlrev_b32_e32 v182, 16, v152
	v_and_b32_e32 v183, 0xffff0000, v152
	v_lshlrev_b32_e32 v152, 16, v153
	v_and_b32_e32 v153, 0xffff0000, v153
	v_lshlrev_b32_e32 v184, 16, v154
	v_and_b32_e32 v185, 0xffff0000, v154
	v_lshlrev_b32_e32 v154, 16, v155
	v_and_b32_e32 v155, 0xffff0000, v155
	v_pk_fma_f32 v[188:189], s[90:91], v[62:63], v[152:153]
	v_pk_fma_f32 v[152:153], s[86:87], v[60:61], v[182:183]
	v_pk_fma_f32 v[182:183], s[90:91], v[54:55], v[154:155]
	v_pk_fma_f32 v[154:155], s[86:87], v[52:53], v[184:185]
	v_mul_f32_e32 v171, v153, v153
	v_mul_f32_e32 v184, v189, v189
	v_fmac_f32_e32 v171, v152, v152
	v_fmac_f32_e32 v184, v188, v188
	v_add_f32_e32 v171, v171, v184
	v_mul_f32_e32 v184, v155, v155
	v_mul_f32_e32 v185, v183, v183
	v_fmac_f32_e32 v184, v154, v154
	v_fmac_f32_e32 v185, v182, v182
	v_add_f32_e32 v184, v184, v185
	v_add_f32_e32 v171, v171, v184
	v_add_f32_e32 v156, v156, v171
	v_cvt_pk_bf16_f32 v152, v152, v153
	v_cvt_pk_bf16_f32 v153, v188, v189
	v_cvt_pk_bf16_f32 v154, v154, v155
	v_cvt_pk_bf16_f32 v155, v182, v183
	global_store_dwordx4 v[180:181], v[152:155], off offset:256
	ds_bpermute_b32 v152, v218, v156
	s_waitcnt lgkmcnt(0)
	v_add_f32_e32 v152, v156, v152
	ds_bpermute_b32 v153, v219, v152
	s_and_saveexec_b64 s[74:75], s[6:7]
	s_cbranch_execz .LBB0_645
	s_waitcnt lgkmcnt(0)
	v_add_f32_e32 v152, v152, v153
	v_mul_f32_e32 v152, 0x4b800000, v152
	v_trunc_f32_e32 v152, v152
	v_mul_f32_e32 v153, 0x2f800000, v152
	v_floor_f32_e32 v153, v153
	v_fmac_f32_e32 v152, 0xcf800000, v153
	v_cvt_u32_f32_e32 v152, v152
	v_cvt_u32_f32_e32 v153, v153
	global_atomic_add_x2 v[172:173], v[152:153], off offset:1024
